# a_ready: flag word read once before the weight-tile DMAs (skips the wait loop when all four owners already arrived); acquire invalidate moved to the arrive
# speedup vs baseline: 1.0015x; 1.0015x over previous
.LBB0_515:
	s_mov_b64 s[8:9], exec
	v_mbcnt_lo_u32_b32 v1, s8, 0
	s_waitcnt vmcnt(0)
	v_mbcnt_hi_u32_b32 v1, s9, v1
	v_cmp_eq_u32_e32 vcc, 0, v1
	s_and_b64 s[4:5], exec, vcc
	s_mov_b64 exec, s[4:5]
	s_cbranch_execz .LBB0_517
	v_readlane_b32 s4, v236, 8
	s_bcnt1_i32_b64 s3, s[8:9]
	s_lshl_b32 s4, s4, 6
	s_add_u32 s4, s72, s4
	s_addc_u32 s5, s73, 0
	v_mov_b32_e32 v1, 0x93000
	v_mov_b32_e32 v2, s3
	global_atomic_add v1, v2, s[4:5]
	buffer_inv sc1

.LBB0_529:
	s_andn2_b64 vcc, exec, s[12:13]
	s_cbranch_vccnz .LBB0_597
	v_ashrrev_i32_e32 v1, 31, v10
	v_lshrrev_b32_e32 v1, 26, v1
	v_add_u32_e32 v1, v10, v1
	v_ashrrev_i32_e32 v2, 6, v1
	v_bfe_i32 v1, v10, 27, 1
	s_waitcnt lgkmcnt(0)
	v_lshlrev_b32_e32 v3, 4, v10
	v_lshrrev_b32_e32 v1, 22, v1
	v_add_u32_e32 v1, v3, v1
	v_and_b32_e32 v1, 0xfffffc00, v1
	v_sub_u32_e32 v1, v3, v1
	v_lshrrev_b32_e32 v4, 4, v1
	v_bitop3_b32 v4, v4, v1, 32 bitop3:0x6c
	v_readlane_b32 s6, v236, 6
	v_ashrrev_i32_e32 v5, 31, v4
	s_add_u32 s3, s72, 0xe00000
	v_readlane_b32 s7, v236, 7
	v_readlane_b32 s5, v236, 8
	v_lshrrev_b32_e32 v5, 26, v5
	s_addc_u32 s4, s73, 0
	s_and_b64 s[10:11], s[6:7], s[10:11]
	s_lshl_b32 s5, s5, 6
	v_add_u32_e32 v5, v4, v5
	s_add_u32 s5, s72, s5
	v_ashrrev_i32_e32 v6, 6, v5
	v_and_b32_e32 v5, 0xc0, v5
	s_addc_u32 s6, s73, 0
	v_sub_u32_e32 v4, v4, v5
	v_mov_b32_e32 v5, 1
	s_add_u32 s5, s5, 0x93000
	v_lshlrev_b32_e32 v1, 3, v2
	v_lshlrev_b32_e32 v2, 5, v2
	v_ashrrev_i16_sdwa v4, v5, sext(v4) dst_sel:DWORD dst_unused:UNUSED_PAD src0_sel:DWORD src1_sel:BYTE_0
	s_addc_u32 s12, s6, 0
	v_and_b32_e32 v1, -16, v1
	v_and_b32_e32 v2, 32, v2
	v_bfe_i32 v4, v4, 0, 16
	v_add_u32_e32 v3, 0x2000, v3
	s_and_b64 s[6:7], s[10:11], exec
	v_add_u32_e32 v1, v6, v1
	v_add_lshl_u32 v2, v2, v4, 1
	v_ashrrev_i32_e32 v4, 31, v3
	s_cselect_b32 s13, s12, 0
	s_cselect_b32 s12, s5, 0
	v_lshlrev_b32_e32 v7, 1, v1
	v_lshrrev_b32_e32 v8, 2, v1
	v_and_b32_e32 v6, 3, v6
	s_mov_b32 s5, 0x1fffe0
	v_lshrrev_b32_e32 v4, 22, v4
	v_and_b32_e32 v7, 24, v7
	v_and_b32_e32 v8, 4, v8
	v_and_or_b32 v6, v1, s5, v6
	v_add_u32_e32 v4, v3, v4
	v_or3_b32 v6, v6, v8, v7
	v_ashrrev_i32_e32 v4, 10, v4
	v_lshl_add_u32 v154, v6, 11, v2
	v_mul_i32_i24_e32 v6, 0x400, v4
	v_sub_u32_e32 v3, v3, v6
	v_lshrrev_b32_e32 v6, 4, v3
	v_bitop3_b32 v6, v6, v3, 32 bitop3:0x6c
	v_ashrrev_i32_e32 v7, 31, v6
	v_lshrrev_b32_e32 v7, 26, v7
	v_lshlrev_b32_e32 v3, 3, v4
	v_add_u32_e32 v7, v6, v7
	v_and_b32_e32 v3, -16, v3
	v_ashrrev_i32_e32 v8, 6, v7
	v_add_u32_e32 v3, v8, v3
	v_and_b32_e32 v8, 3, v8
	s_ashr_i32 s20, s24, 6
	s_ashr_i32 s43, s42, 31
	v_and_b32_e32 v7, 0xc0, v7
	v_and_or_b32 v8, v3, s5, v8
	s_lshl_b32 s5, s20, 10
	s_lshl_b64 s[6:7], s[42:43], 19
	v_sub_u32_e32 v6, v6, v7
	s_add_u32 s44, s3, s6
	v_lshlrev_b32_e32 v4, 5, v4
	v_ashrrev_i16_sdwa v5, v5, sext(v6) dst_sel:DWORD dst_unused:UNUSED_PAD src0_sel:DWORD src1_sel:BYTE_0
	v_lshlrev_b32_e32 v6, 1, v3
	v_lshrrev_b32_e32 v7, 2, v3
	s_addc_u32 s45, s4, s7
	s_add_i32 s33, s5, 0
	v_and_b32_e32 v4, 32, v4
	v_bfe_i32 v5, v5, 0, 16
	v_and_b32_e32 v6, 24, v6
	v_and_b32_e32 v7, 4, v7
	s_cmp_lg_u64 s[12:13], 0
	s_cbranch_scc0 .Lpp_skip_0
	s_mov_b64 s[98:99], exec
	s_and_b64 exec, exec, s[22:23]
	v_mov_b32_e32 v238, 0
	global_load_dword v239, v238, s[12:13] sc1
	s_mov_b64 exec, s[98:99]
.Lpp_skip_0:
	s_add_i32 m0, s33, 0x10000
	v_or3_b32 v6, v8, v7, v6
	v_add_lshl_u32 v4, v4, v5, 1
	global_load_lds_dwordx4 v154, s[44:45]
	s_add_i32 m0, s33, 0x12000
	v_lshl_add_u32 v156, v6, 11, v4
	s_add_u32 s6, s44, 0x40000
	global_load_lds_dwordx4 v156, s[44:45]
	s_addc_u32 s7, s45, 0
	s_add_i32 m0, s33, 0x14000
	v_mov_b32_e32 v159, 0
	global_load_lds_dwordx4 v154, s[6:7]
	s_add_i32 m0, s33, 0x16000
	s_cmp_eq_u32 s42, s84
	global_load_lds_dwordx4 v156, s[6:7]
	s_cselect_b64 s[6:7], -1, 0
	s_and_b64 s[6:7], s[10:11], s[6:7]
	v_mov_b32_e32 v155, v159
	s_andn2_b64 vcc, exec, s[6:7]
	v_mov_b32_e32 v157, v159
	s_cbranch_vccnz .LBB0_545
	s_and_saveexec_b64 s[6:7], s[22:23]
	s_cbranch_execz .LBB0_544
	s_mov_b32 s16, 0x400001
	s_waitcnt vmcnt(4)
	v_cmp_lt_u32_e32 vcc, 3, v239
	s_waitcnt lgkmcnt(0)
	s_cbranch_vccnz .Lpp_fast_0
	v_mov_b32_e32 v5, 0
	s_branch .LBB0_534

.Lpp_fast_0:
.LBB0_544:
	s_or_b64 exec, exec, s[6:7]
	s_barrier

.LBB0_656:
	s_mov_b64 s[10:11], exec
	v_mbcnt_lo_u32_b32 v1, s10, 0
	s_waitcnt vmcnt(0)
	v_mbcnt_hi_u32_b32 v1, s11, v1
	v_cmp_eq_u32_e32 vcc, 0, v1
	s_and_b64 s[4:5], exec, vcc
	s_mov_b64 exec, s[4:5]
	s_cbranch_execz .LBB0_658
	v_readlane_b32 s4, v236, 8
	s_bcnt1_i32_b64 s3, s[10:11]
	s_lshl_b32 s4, s4, 6
	s_add_u32 s4, s72, s4
	s_addc_u32 s5, s73, 0
	v_mov_b32_e32 v1, 0x94000
	v_mov_b32_e32 v2, s3
	global_atomic_add v1, v2, s[4:5]
	buffer_inv sc1

.LBB0_669:
	s_andn2_b64 vcc, exec, s[12:13]
	s_cbranch_vccnz .LBB0_718
	v_ashrrev_i32_e32 v1, 31, v10
	v_lshrrev_b32_e32 v1, 26, v1
	v_add_u32_e32 v1, v10, v1
	v_ashrrev_i32_e32 v2, 6, v1
	v_bfe_i32 v1, v10, 27, 1
	s_waitcnt lgkmcnt(0)
	v_lshlrev_b32_e32 v3, 4, v10
	v_lshrrev_b32_e32 v1, 22, v1
	v_add_u32_e32 v1, v3, v1
	v_and_b32_e32 v1, 0xfffffc00, v1
	v_sub_u32_e32 v1, v3, v1
	v_lshrrev_b32_e32 v4, 4, v1
	v_readlane_b32 s10, v236, 6
	v_bitop3_b32 v4, v4, v1, 32 bitop3:0x6c
	s_add_u32 s3, s72, 0x1700000
	v_readlane_b32 s11, v236, 7
	v_ashrrev_i32_e32 v5, 31, v4
	s_addc_u32 s4, s73, 0
	s_and_b64 s[24:25], s[10:11], s[0:1]
	v_readlane_b32 s0, v236, 8
	v_lshrrev_b32_e32 v5, 26, v5
	s_lshl_b32 s0, s0, 6
	v_add_u32_e32 v5, v4, v5
	s_add_u32 s0, s72, s0
	v_ashrrev_i32_e32 v6, 6, v5
	v_and_b32_e32 v5, 0xc0, v5
	s_addc_u32 s1, s73, 0
	v_sub_u32_e32 v4, v4, v5
	v_mov_b32_e32 v5, 1
	s_add_u32 s5, s0, 0x94000
	v_lshlrev_b32_e32 v1, 3, v2
	v_lshlrev_b32_e32 v2, 5, v2
	v_ashrrev_i16_sdwa v4, v5, sext(v4) dst_sel:DWORD dst_unused:UNUSED_PAD src0_sel:DWORD src1_sel:BYTE_0
	s_addc_u32 s7, s1, 0
	v_and_b32_e32 v1, -16, v1
	v_and_b32_e32 v2, 32, v2
	v_bfe_i32 v4, v4, 0, 16
	v_add_u32_e32 v3, 0x2000, v3
	s_and_b64 s[0:1], s[24:25], exec
	v_add_u32_e32 v1, v6, v1
	v_add_lshl_u32 v2, v2, v4, 1
	v_ashrrev_i32_e32 v4, 31, v3
	v_lshlrev_b32_e32 v7, 1, v1
	v_lshrrev_b32_e32 v8, 2, v1
	v_and_b32_e32 v6, 3, v6
	s_mov_b32 s0, 0x1fffe0
	v_lshrrev_b32_e32 v4, 22, v4
	v_and_b32_e32 v7, 24, v7
	v_and_b32_e32 v8, 4, v8
	v_and_or_b32 v6, v1, s0, v6
	v_add_u32_e32 v4, v3, v4
	v_or3_b32 v6, v6, v8, v7
	v_ashrrev_i32_e32 v4, 10, v4
	v_lshl_add_u32 v130, v6, 11, v2
	v_mul_i32_i24_e32 v6, 0x400, v4
	v_sub_u32_e32 v3, v3, v6
	v_lshrrev_b32_e32 v6, 4, v3
	v_bitop3_b32 v6, v6, v3, 32 bitop3:0x6c
	v_ashrrev_i32_e32 v7, 31, v6
	v_lshrrev_b32_e32 v7, 26, v7
	v_lshlrev_b32_e32 v3, 3, v4
	v_add_u32_e32 v7, v6, v7
	v_and_b32_e32 v3, -16, v3
	v_ashrrev_i32_e32 v8, 6, v7
	s_cselect_b32 s27, s7, 0
	s_cselect_b32 s26, s5, 0
	v_add_u32_e32 v3, v8, v3
	v_and_b32_e32 v8, 3, v8
	s_ashr_i32 s15, s14, 6
	s_ashr_i32 s7, s6, 31
	v_and_b32_e32 v7, 0xc0, v7
	v_and_or_b32 v8, v3, s0, v8
	s_lshl_b32 s5, s15, 10
	s_lshl_b64 s[0:1], s[6:7], 19
	v_sub_u32_e32 v6, v6, v7
	s_add_u32 s0, s3, s0
	v_lshlrev_b32_e32 v4, 5, v4
	v_ashrrev_i16_sdwa v5, v5, sext(v6) dst_sel:DWORD dst_unused:UNUSED_PAD src0_sel:DWORD src1_sel:BYTE_0
	v_lshlrev_b32_e32 v6, 1, v3
	v_lshrrev_b32_e32 v7, 2, v3
	s_addc_u32 s1, s4, s1
	s_add_i32 s33, s5, 0
	v_and_b32_e32 v4, 32, v4
	v_bfe_i32 v5, v5, 0, 16
	v_and_b32_e32 v6, 24, v6
	v_and_b32_e32 v7, 4, v7
	s_cmp_lg_u64 s[26:27], 0
	s_cbranch_scc0 .Lpp_skip_1
	s_mov_b64 s[98:99], exec
	s_and_b64 exec, exec, s[22:23]
	v_mov_b32_e32 v238, 0
	global_load_dword v239, v238, s[26:27] sc1
	s_mov_b64 exec, s[98:99]
.Lpp_skip_1:
	s_add_i32 m0, s33, 0x10000
	v_or3_b32 v6, v8, v7, v6
	v_add_lshl_u32 v4, v4, v5, 1
	global_load_lds_dwordx4 v130, s[0:1]
	s_add_i32 m0, s33, 0x12000
	v_lshl_add_u32 v132, v6, 11, v4
	s_add_u32 s10, s0, 0x40000
	global_load_lds_dwordx4 v132, s[0:1]
	s_addc_u32 s11, s1, 0
	s_add_i32 m0, s33, 0x14000
	v_mov_b32_e32 v135, 0
	global_load_lds_dwordx4 v130, s[10:11]
	s_add_i32 m0, s33, 0x16000
	s_cmp_eq_u32 s6, s84
	global_load_lds_dwordx4 v132, s[10:11]
	s_cselect_b64 s[10:11], -1, 0
	s_and_b64 s[10:11], s[24:25], s[10:11]
	v_mov_b32_e32 v131, v135
	s_andn2_b64 vcc, exec, s[10:11]
	v_mov_b32_e32 v133, v135
	s_cbranch_vccnz .LBB0_682
	s_and_saveexec_b64 s[10:11], s[22:23]
	s_cbranch_execz .LBB0_681
	s_mov_b32 s7, 0x400001
	s_waitcnt vmcnt(4)
	v_cmp_lt_u32_e32 vcc, 3, v239
	s_waitcnt lgkmcnt(0)
	s_cbranch_vccnz .Lpp_fast_1
	v_mov_b32_e32 v5, 0
	s_branch .LBB0_674

.Lpp_fast_1:
.LBB0_681:
	s_or_b64 exec, exec, s[10:11]
	s_barrier

.LBB0_777:
	s_mov_b64 s[8:9], exec
	v_mbcnt_lo_u32_b32 v1, s8, 0
	s_waitcnt vmcnt(0)
	v_mbcnt_hi_u32_b32 v1, s9, v1
	v_cmp_eq_u32_e32 vcc, 0, v1
	s_and_b64 s[4:5], exec, vcc
	s_mov_b64 exec, s[4:5]
	s_cbranch_execz .LBB0_779
	v_readlane_b32 s4, v236, 8
	s_bcnt1_i32_b64 s3, s[8:9]
	s_lshl_b32 s4, s4, 6
	s_add_u32 s4, s72, s4
	s_addc_u32 s5, s73, 0
	v_mov_b32_e32 v1, 0x95000
	v_mov_b32_e32 v2, s3
	global_atomic_add v1, v2, s[4:5]
	buffer_inv sc1

.LBB0_791:
	s_andn2_b64 vcc, exec, s[8:9]
	s_cbranch_vccnz .LBB0_859
	v_ashrrev_i32_e32 v1, 31, v10
	v_lshrrev_b32_e32 v1, 26, v1
	v_add_u32_e32 v1, v10, v1
	v_ashrrev_i32_e32 v2, 6, v1
	v_bfe_i32 v1, v10, 27, 1
	s_waitcnt lgkmcnt(0)
	v_lshlrev_b32_e32 v3, 4, v10
	v_lshrrev_b32_e32 v1, 22, v1
	v_add_u32_e32 v1, v3, v1
	v_and_b32_e32 v1, 0xfffffc00, v1
	v_sub_u32_e32 v1, v3, v1
	v_lshrrev_b32_e32 v4, 4, v1
	v_bitop3_b32 v4, v4, v1, 32 bitop3:0x6c
	v_readlane_b32 s6, v236, 6
	v_ashrrev_i32_e32 v5, 31, v4
	s_add_u32 s3, s72, 0x2700000
	v_readlane_b32 s7, v236, 7
	v_readlane_b32 s5, v236, 8
	v_lshrrev_b32_e32 v5, 26, v5
	s_addc_u32 s4, s73, 0
	s_and_b64 s[8:9], s[6:7], s[18:19]
	s_lshl_b32 s5, s5, 6
	v_add_u32_e32 v5, v4, v5
	s_add_u32 s5, s72, s5
	v_ashrrev_i32_e32 v6, 6, v5
	v_and_b32_e32 v5, 0xc0, v5
	s_addc_u32 s6, s73, 0
	v_sub_u32_e32 v4, v4, v5
	v_mov_b32_e32 v5, 1
	s_add_u32 s5, s5, 0x95000
	v_lshlrev_b32_e32 v1, 3, v2
	v_lshlrev_b32_e32 v2, 5, v2
	v_ashrrev_i16_sdwa v4, v5, sext(v4) dst_sel:DWORD dst_unused:UNUSED_PAD src0_sel:DWORD src1_sel:BYTE_0
	s_addc_u32 s10, s6, 0
	v_and_b32_e32 v1, -16, v1
	v_and_b32_e32 v2, 32, v2
	v_bfe_i32 v4, v4, 0, 16
	v_add_u32_e32 v3, 0x2000, v3
	s_and_b64 s[6:7], s[8:9], exec
	v_add_u32_e32 v1, v6, v1
	v_add_lshl_u32 v2, v2, v4, 1
	v_ashrrev_i32_e32 v4, 31, v3
	s_cselect_b32 s11, s10, 0
	s_cselect_b32 s10, s5, 0
	v_lshlrev_b32_e32 v7, 1, v1
	v_lshrrev_b32_e32 v8, 2, v1
	v_and_b32_e32 v6, 3, v6
	s_mov_b32 s5, 0x7ffe0
	v_lshrrev_b32_e32 v4, 22, v4
	v_and_b32_e32 v7, 24, v7
	v_and_b32_e32 v8, 4, v8
	v_and_or_b32 v6, v1, s5, v6
	v_add_u32_e32 v4, v3, v4
	v_or3_b32 v6, v6, v8, v7
	v_ashrrev_i32_e32 v4, 10, v4
	v_lshl_add_u32 v154, v6, 13, v2
	v_mul_i32_i24_e32 v6, 0x400, v4
	v_sub_u32_e32 v3, v3, v6
	v_lshrrev_b32_e32 v6, 4, v3
	v_bitop3_b32 v6, v6, v3, 32 bitop3:0x6c
	v_ashrrev_i32_e32 v7, 31, v6
	v_lshrrev_b32_e32 v7, 26, v7
	v_lshlrev_b32_e32 v3, 3, v4
	v_add_u32_e32 v7, v6, v7
	v_and_b32_e32 v3, -16, v3
	v_ashrrev_i32_e32 v8, 6, v7
	v_add_u32_e32 v3, v8, v3
	v_and_b32_e32 v8, 3, v8
	s_ashr_i32 s18, s20, 6
	s_ashr_i32 s41, s40, 31
	v_and_b32_e32 v7, 0xc0, v7
	v_and_or_b32 v8, v3, s5, v8
	s_lshl_b32 s5, s18, 10
	s_lshl_b64 s[6:7], s[40:41], 21
	v_sub_u32_e32 v6, v6, v7
	s_add_u32 s42, s3, s6
	v_lshlrev_b32_e32 v4, 5, v4
	v_ashrrev_i16_sdwa v5, v5, sext(v6) dst_sel:DWORD dst_unused:UNUSED_PAD src0_sel:DWORD src1_sel:BYTE_0
	v_lshlrev_b32_e32 v6, 1, v3
	v_lshrrev_b32_e32 v7, 2, v3
	s_addc_u32 s43, s4, s7
	s_add_i32 s33, s5, 0
	v_and_b32_e32 v4, 32, v4
	v_bfe_i32 v5, v5, 0, 16
	v_and_b32_e32 v6, 24, v6
	v_and_b32_e32 v7, 4, v7
	s_cmp_lg_u64 s[10:11], 0
	s_cbranch_scc0 .Lpp_skip_2
	s_mov_b64 s[98:99], exec
	s_and_b64 exec, exec, s[22:23]
	v_mov_b32_e32 v238, 0
	global_load_dword v239, v238, s[10:11] sc1
	s_mov_b64 exec, s[98:99]
.Lpp_skip_2:
	s_add_i32 m0, s33, 0x10000
	v_or3_b32 v6, v8, v7, v6
	v_add_lshl_u32 v4, v4, v5, 1
	global_load_lds_dwordx4 v154, s[42:43]
	s_add_i32 m0, s33, 0x12000
	v_lshl_add_u32 v156, v6, 13, v4
	s_add_u32 s6, s42, 0x100000
	global_load_lds_dwordx4 v156, s[42:43]
	s_addc_u32 s7, s43, 0
	s_add_i32 m0, s33, 0x14000
	v_mov_b32_e32 v159, 0
	global_load_lds_dwordx4 v154, s[6:7]
	s_add_i32 m0, s33, 0x16000
	s_cmp_eq_u32 s40, s84
	global_load_lds_dwordx4 v156, s[6:7]
	s_cselect_b64 s[6:7], -1, 0
	s_and_b64 s[6:7], s[8:9], s[6:7]
	v_mov_b32_e32 v155, v159
	s_andn2_b64 vcc, exec, s[6:7]
	v_mov_b32_e32 v157, v159
	s_cbranch_vccnz .LBB0_807
	s_and_saveexec_b64 s[6:7], s[22:23]
	s_cbranch_execz .LBB0_806
	s_mov_b32 s14, 0x400001
	s_waitcnt vmcnt(4)
	v_cmp_lt_u32_e32 vcc, 3, v239
	s_waitcnt lgkmcnt(0)
	s_cbranch_vccnz .Lpp_fast_2
	v_mov_b32_e32 v5, 0
	s_branch .LBB0_796

.LBB0_1761:
	s_mov_b64 s[10:11], exec
	v_mbcnt_lo_u32_b32 v0, s10, 0
	s_waitcnt vmcnt(0)
	v_mbcnt_hi_u32_b32 v0, s11, v0
	v_cmp_eq_u32_e32 vcc, 0, v0
	s_and_b64 s[4:5], exec, vcc
	s_mov_b64 exec, s[4:5]
	s_cbranch_execz .LBB0_1763
	v_readlane_b32 s4, v236, 8
	s_bcnt1_i32_b64 s3, s[10:11]
	s_lshl_b32 s4, s4, 6
	s_add_u32 s4, s72, s4
	s_addc_u32 s5, s73, 0
	v_mov_b32_e32 v0, 0x9a000
	v_mov_b32_e32 v1, s3
	global_atomic_add v0, v1, s[4:5]
	buffer_inv sc1

.LBB0_1775:
	s_andn2_b64 vcc, exec, s[12:13]
	s_cbranch_vccnz .LBB0_1827
	v_ashrrev_i32_e32 v0, 31, v8
	v_lshrrev_b32_e32 v0, 26, v0
	v_add_u32_e32 v0, v8, v0
	s_waitcnt lgkmcnt(0)
	v_ashrrev_i32_e32 v1, 6, v0
	v_bfe_i32 v0, v8, 27, 1
	v_lshlrev_b32_e32 v2, 4, v8
	v_lshrrev_b32_e32 v0, 22, v0
	v_add_u32_e32 v0, v2, v0
	v_and_b32_e32 v0, 0xfffffc00, v0
	v_sub_u32_e32 v0, v2, v0
	v_lshrrev_b32_e32 v3, 4, v0
	v_readlane_b32 s10, v236, 6
	v_bitop3_b32 v3, v3, v0, 32 bitop3:0x6c
	s_add_u32 s3, s72, 0x1f00000
	v_readlane_b32 s11, v236, 7
	v_ashrrev_i32_e32 v4, 31, v3
	s_addc_u32 s4, s73, 0
	s_and_b64 s[24:25], s[10:11], s[0:1]
	v_readlane_b32 s0, v236, 8
	v_lshrrev_b32_e32 v4, 26, v4
	s_lshl_b32 s0, s0, 6
	v_add_u32_e32 v4, v3, v4
	s_add_u32 s0, s72, s0
	v_ashrrev_i32_e32 v5, 6, v4
	v_and_b32_e32 v4, 0xc0, v4
	s_addc_u32 s1, s73, 0
	v_sub_u32_e32 v3, v3, v4
	v_mov_b32_e32 v4, 1
	s_add_u32 s5, s0, 0x9a000
	v_lshlrev_b32_e32 v0, 3, v1
	v_lshlrev_b32_e32 v1, 5, v1
	v_ashrrev_i16_sdwa v3, v4, sext(v3) dst_sel:DWORD dst_unused:UNUSED_PAD src0_sel:DWORD src1_sel:BYTE_0
	s_addc_u32 s7, s1, 0
	v_and_b32_e32 v0, -16, v0
	v_and_b32_e32 v1, 32, v1
	v_bfe_i32 v3, v3, 0, 16
	v_add_u32_e32 v2, 0x2000, v2
	s_and_b64 s[0:1], s[24:25], exec
	v_add_u32_e32 v0, v5, v0
	v_add_lshl_u32 v1, v1, v3, 1
	v_ashrrev_i32_e32 v3, 31, v2
	v_lshlrev_b32_e32 v6, 1, v0
	v_lshrrev_b32_e32 v7, 2, v0
	v_and_b32_e32 v5, 3, v5
	s_mov_b32 s0, 0x1fffe0
	v_lshrrev_b32_e32 v3, 22, v3
	v_and_b32_e32 v6, 24, v6
	v_and_b32_e32 v7, 4, v7
	v_and_or_b32 v5, v0, s0, v5
	v_add_u32_e32 v3, v2, v3
	v_or3_b32 v5, v5, v7, v6
	v_ashrrev_i32_e32 v3, 10, v3
	v_lshl_add_u32 v128, v5, 11, v1
	v_mul_i32_i24_e32 v5, 0x400, v3
	v_sub_u32_e32 v2, v2, v5
	v_lshrrev_b32_e32 v5, 4, v2
	v_bitop3_b32 v5, v5, v2, 32 bitop3:0x6c
	v_ashrrev_i32_e32 v6, 31, v5
	v_lshrrev_b32_e32 v6, 26, v6
	v_lshlrev_b32_e32 v2, 3, v3
	v_add_u32_e32 v6, v5, v6
	v_and_b32_e32 v2, -16, v2
	v_ashrrev_i32_e32 v7, 6, v6
	s_cselect_b32 s27, s7, 0
	s_cselect_b32 s26, s5, 0
	v_add_u32_e32 v2, v7, v2
	v_and_b32_e32 v7, 3, v7
	s_ashr_i32 s15, s14, 6
	s_ashr_i32 s7, s6, 31
	v_and_b32_e32 v6, 0xc0, v6
	v_and_or_b32 v7, v2, s0, v7
	s_lshl_b32 s5, s15, 10
	s_lshl_b64 s[0:1], s[6:7], 19
	v_sub_u32_e32 v5, v5, v6
	s_add_u32 s0, s3, s0
	v_lshlrev_b32_e32 v3, 5, v3
	v_ashrrev_i16_sdwa v4, v4, sext(v5) dst_sel:DWORD dst_unused:UNUSED_PAD src0_sel:DWORD src1_sel:BYTE_0
	v_lshlrev_b32_e32 v5, 1, v2
	v_lshrrev_b32_e32 v6, 2, v2
	s_addc_u32 s1, s4, s1
	s_add_i32 s33, s5, 0
	v_and_b32_e32 v3, 32, v3
	v_bfe_i32 v4, v4, 0, 16
	v_and_b32_e32 v5, 24, v5
	v_and_b32_e32 v6, 4, v6
	s_cmp_lg_u64 s[26:27], 0
	s_cbranch_scc0 .Lpp_skip_3
	s_mov_b64 s[98:99], exec
	s_and_b64 exec, exec, s[22:23]
	v_mov_b32_e32 v238, 0
	global_load_dword v239, v238, s[26:27] sc1
	s_mov_b64 exec, s[98:99]
.Lpp_skip_3:
	s_add_i32 m0, s33, 0x10000
	v_or3_b32 v5, v7, v6, v5
	v_add_lshl_u32 v3, v3, v4, 1
	global_load_lds_dwordx4 v128, s[0:1]
	s_add_i32 m0, s33, 0x12000
	v_lshl_add_u32 v130, v5, 11, v3
	s_add_u32 s10, s0, 0x40000
	global_load_lds_dwordx4 v130, s[0:1]
	s_addc_u32 s11, s1, 0
	s_add_i32 m0, s33, 0x14000
	v_mov_b32_e32 v133, 0
	global_load_lds_dwordx4 v128, s[10:11]
	s_add_i32 m0, s33, 0x16000
	s_cmp_eq_u32 s6, s84
	global_load_lds_dwordx4 v130, s[10:11]
	s_cselect_b64 s[10:11], -1, 0
	s_and_b64 s[10:11], s[24:25], s[10:11]
	v_mov_b32_e32 v129, v133
	s_andn2_b64 vcc, exec, s[10:11]
	v_mov_b32_e32 v131, v133
	s_cbranch_vccnz .LBB0_1791
	s_and_saveexec_b64 s[10:11], s[22:23]
	s_cbranch_execz .LBB0_1790
	s_mov_b32 s7, 0x400001
	s_waitcnt vmcnt(4)
	v_cmp_lt_u32_e32 vcc, 3, v239
	s_waitcnt lgkmcnt(0)
	s_cbranch_vccnz .Lpp_fast_3
	v_mov_b32_e32 v4, 0
	s_branch .LBB0_1780

.LBB0_1886:
	s_mov_b64 s[8:9], exec
	v_mbcnt_lo_u32_b32 v0, s8, 0
	s_waitcnt vmcnt(0)
	v_mbcnt_hi_u32_b32 v0, s9, v0
	v_cmp_eq_u32_e32 vcc, 0, v0
	s_and_b64 s[4:5], exec, vcc
	s_mov_b64 exec, s[4:5]
	s_cbranch_execz .LBB0_1888
	v_readlane_b32 s4, v236, 8
	s_bcnt1_i32_b64 s3, s[8:9]
	s_lshl_b32 s4, s4, 6
	s_add_u32 s4, s72, s4
	s_addc_u32 s5, s73, 0
	v_mov_b32_e32 v0, 0x9b000
	v_mov_b32_e32 v1, s3
	global_atomic_add v0, v1, s[4:5]
	buffer_inv sc1

.LBB0_2003:
	s_and_b64 vcc, exec, s[4:5]
	s_cbranch_vccz .LBB0_2015
	s_cmp_gt_i32 s84, 3
	v_readfirstlane_b32 s38, v182
	s_cbranch_scc1 .LBB0_2015
	v_ashrrev_i32_e32 v0, 31, v182
	v_lshrrev_b32_e32 v0, 26, v0
	v_add_u32_e32 v0, v182, v0
	v_ashrrev_i32_e32 v1, 6, v0
	v_bfe_i32 v0, v182, 27, 1
	v_lshlrev_b32_e32 v2, 4, v182
	v_lshrrev_b32_e32 v0, 22, v0
	v_add_u32_e32 v0, v2, v0
	v_and_b32_e32 v0, 0xfffffc00, v0
	v_sub_u32_e32 v0, v2, v0
	v_lshrrev_b32_e32 v3, 4, v0
	v_bitop3_b32 v3, v3, v0, 32 bitop3:0x6c
	v_ashrrev_i32_e32 v4, 31, v3
	v_lshrrev_b32_e32 v4, 26, v4
	v_add_u32_e32 v4, v3, v4
	v_ashrrev_i32_e32 v5, 6, v4
	v_and_b32_e32 v4, 0xc0, v4
	v_sub_u32_e32 v3, v3, v4
	v_mov_b32_e32 v4, 1
	v_lshlrev_b32_e32 v0, 3, v1
	v_lshlrev_b32_e32 v1, 5, v1
	v_ashrrev_i16_sdwa v3, v4, sext(v3) dst_sel:DWORD dst_unused:UNUSED_PAD src0_sel:DWORD src1_sel:BYTE_0
	v_and_b32_e32 v1, 32, v1
	v_bfe_i32 v3, v3, 0, 16
	v_add_u32_e32 v2, 0x2000, v2
	v_add_lshl_u32 v1, v1, v3, 1
	v_ashrrev_i32_e32 v3, 31, v2
	v_lshrrev_b32_e32 v3, 22, v3
	v_add_u32_e32 v3, v2, v3
	v_ashrrev_i32_e32 v3, 10, v3
	v_mul_i32_i24_e32 v6, 0x400, v3
	v_sub_u32_e32 v2, v2, v6
	v_lshrrev_b32_e32 v6, 4, v2
	v_bitop3_b32 v6, v6, v2, 32 bitop3:0x6c
	v_ashrrev_i32_e32 v7, 31, v6
	v_lshrrev_b32_e32 v7, 26, v7
	v_add_u32_e32 v7, v6, v7
	v_ashrrev_i32_e32 v8, 6, v7
	v_and_b32_e32 v7, 0xc0, v7
	v_lshlrev_b32_e32 v2, 3, v3
	v_sub_u32_e32 v6, v6, v7
	v_and_b32_e32 v2, -16, v2
	v_lshlrev_b32_e32 v3, 5, v3
	v_ashrrev_i16_sdwa v4, v4, sext(v6) dst_sel:DWORD dst_unused:UNUSED_PAD src0_sel:DWORD src1_sel:BYTE_0
	v_add_u32_e32 v2, v8, v2
	v_and_b32_e32 v3, 32, v3
	v_bfe_i32 v4, v4, 0, 16
	v_add_lshl_u32 v3, v3, v4, 1
	v_and_b32_e32 v4, 3, v8
	s_mov_b32 s2, 0x7ffe0
	v_lshrrev_b32_e32 v6, 2, v2
	v_lshlrev_b32_e32 v7, 1, v2
	v_and_or_b32 v4, v2, s2, v4
	v_and_b32_e32 v6, 4, v6
	v_and_b32_e32 v7, 24, v7
	v_and_b32_e32 v0, -16, v0
	v_or3_b32 v4, v4, v6, v7
	s_ashr_i32 s33, s38, 6
	v_add_u32_e32 v0, v5, v0
	v_lshl_add_u32 v128, v4, 13, v3
	v_and_b32_e32 v4, 3, v5
	s_ashr_i32 s85, s84, 31
	s_lshl_b32 s39, s33, 10
	v_and_or_b32 v4, v0, s2, v4
	v_lshrrev_b32_e32 v5, 2, v0
	v_lshlrev_b32_e32 v6, 1, v0
	s_lshl_b64 s[2:3], s[84:85], 21
	v_and_b32_e32 v5, 4, v5
	v_and_b32_e32 v6, 24, v6
	s_add_u32 s4, s61, s2
	v_or3_b32 v4, v4, v5, v6
	s_addc_u32 s5, s62, s3
	s_add_i32 s40, s39, 0
	v_lshl_add_u32 v130, v4, 13, v1
	s_cmp_lg_u64 s[14:15], 0
	s_cbranch_scc0 .Lpp_skip_4
	s_mov_b64 s[98:99], exec
	s_and_b64 exec, exec, s[22:23]
	v_mov_b32_e32 v238, 0
	global_load_dword v239, v238, s[14:15] sc1
	s_mov_b64 exec, s[98:99]
.Lpp_skip_4:
	s_add_i32 m0, s40, 0x10000
	v_mov_b32_e32 v133, 0
	global_load_lds_dwordx4 v130, s[4:5]
	s_add_i32 m0, s40, 0x12000
	s_add_u32 s2, s4, 0x100000
	global_load_lds_dwordx4 v128, s[4:5]
	s_addc_u32 s3, s5, 0
	s_add_i32 m0, s40, 0x14000
	v_mov_b32_e32 v131, v133
	global_load_lds_dwordx4 v130, s[2:3]
	s_add_i32 m0, s40, 0x16000
	s_andn2_b64 vcc, exec, s[18:19]
	global_load_lds_dwordx4 v128, s[2:3]
	v_mov_b32_e32 v129, v133
	s_cbranch_vccnz .LBB0_2018
	s_and_saveexec_b64 s[2:3], s[22:23]
	s_cbranch_execz .LBB0_2017
	s_mov_b32 s16, 0x400001
	s_waitcnt vmcnt(4)
	v_cmp_lt_u32_e32 vcc, 3, v239
	s_waitcnt lgkmcnt(0)
	s_cbranch_vccnz .Lpp_fast_4
	v_mov_b32_e32 v4, 0
	s_branch .LBB0_2009

.Lpp_fast_4:
.LBB0_2017:
	s_or_b64 exec, exec, s[2:3]
	s_barrier
